# inproj rotary epilogue: pos loads batched, store-completion waits removed
# speedup vs baseline: 1.1035x; 1.0074x over previous
.LBB0_358:
	s_and_b64 vcc, exec, s[4:5]
	s_cbranch_vccz .LBB0_125
	v_ashrrev_i32_e32 v139, 31, v138
	v_lshl_add_u64 v[130:131], v[138:139], 2, s[16:17]
	global_load_dword v129, v[130:131], off
	global_load_dword v242, v[130:131], off offset:64
	global_load_dword v243, v[130:131], off offset:128
	global_load_dword v244, v[130:131], off offset:192
	global_load_dword v245, v[130:131], off offset:256
	global_load_dword v246, v[130:131], off offset:320
	global_load_dword v247, v[130:131], off offset:384
	global_load_dword v248, v[130:131], off offset:448
	v_lshlrev_b32_e32 v156, 3, v149
	v_mov_b32_e32 v141, v137
	v_lshlrev_b32_e32 v136, 4, v149
	v_lshl_add_u64 v[132:133], v[140:141], 1, s[12:13]
	v_cvt_f32_ubyte0_e32 v134, v156
	v_cmp_lt_i32_e32 vcc, s41, v140
	v_or_b32_e32 v135, 1, v156
	v_lshl_add_u64 v[132:133], v[132:133], 0, v[136:137]
	v_mul_f32_e32 v136, 0xbed49a78, v134
	v_cndmask_b32_e32 v128, 1.0, v146, vcc
	v_or_b32_e32 v139, 2, v156
	v_or_b32_e32 v140, 3, v156
	v_or_b32_e32 v141, 4, v156
	v_cvt_f32_ubyte0_e32 v135, v135
	v_cmp_gt_f32_e32 vcc, s42, v136
	v_cvt_f32_ubyte0_e32 v139, v139
	v_cvt_f32_ubyte0_e32 v140, v140
	v_cvt_f32_ubyte0_e32 v141, v141
	v_cndmask_b32_e32 v136, 0, v147, vcc
	v_mul_f32_e32 v142, 0xbed49a78, v135
	v_mul_f32_e32 v143, 0xbed49a78, v139
	v_mul_f32_e32 v144, 0xbed49a78, v140
	v_mul_f32_e32 v145, 0xbed49a78, v141
	v_fmac_f32_e32 v136, 0xbed49a78, v134
	v_cndmask_b32_e32 v134, 0, v148, vcc
	v_cmp_gt_f32_e32 vcc, s42, v142
	v_cmp_gt_f32_e64 s[2:3], s42, v143
	v_cmp_gt_f32_e64 s[4:5], s42, v144
	v_cndmask_b32_e32 v142, 0, v147, vcc
	v_cmp_gt_f32_e64 s[6:7], s42, v145
	v_cndmask_b32_e64 v143, 0, v147, s[2:3]
	v_cndmask_b32_e64 v144, 0, v147, s[4:5]
	v_cndmask_b32_e64 v145, 0, v147, s[6:7]
	v_fmac_f32_e32 v142, 0xbed49a78, v135
	v_exp_f32_e32 v136, v136
	v_fmac_f32_e32 v143, 0xbed49a78, v139
	v_fmac_f32_e32 v144, 0xbed49a78, v140
	v_fmac_f32_e32 v145, 0xbed49a78, v141
	v_exp_f32_e32 v142, v142
	v_exp_f32_e32 v143, v143
	v_exp_f32_e32 v144, v144
	v_exp_f32_e32 v145, v145
	v_cndmask_b32_e32 v135, 0, v148, vcc
	v_cndmask_b32_e64 v149, 0, v148, s[2:3]
	v_cndmask_b32_e64 v140, 0, v148, s[4:5]
	v_cndmask_b32_e64 v141, 0, v148, s[6:7]
	v_ldexp_f32 v139, v136, v134
	v_ldexp_f32 v136, v142, v135
	v_ldexp_f32 v135, v143, v149
	v_ldexp_f32 v134, v144, v140
	s_waitcnt vmcnt(0)
	v_cvt_f32_i32_e32 v157, v129
	v_ldexp_f32 v129, v145, v141
	v_mul_f32_e32 v140, v139, v157
	v_mul_f32_e32 v141, v136, v157
	v_mul_f32_e32 v142, v135, v157
	v_mul_f32_e32 v143, v134, v157
	v_mul_f32_e32 v145, 0.15915494, v140
	v_mul_f32_e32 v149, 0.15915494, v141
	v_mul_f32_e32 v150, 0.15915494, v142
	v_mul_f32_e32 v151, 0.15915494, v143
	v_rndne_f32_e32 v145, v145
	v_rndne_f32_e32 v149, v149
	v_rndne_f32_e32 v150, v150
	v_rndne_f32_e32 v151, v151
	v_fma_f32 v145, v140, 0.15915494, -v145
	v_fma_f32 v149, v141, 0.15915494, -v149
	v_fma_f32 v150, v142, 0.15915494, -v150
	v_fma_f32 v151, v143, 0.15915494, -v151
	v_fmac_f32_e32 v145, 0x31dc9c88, v140
	v_fmac_f32_e32 v149, 0x31dc9c88, v141
	v_fmac_f32_e32 v150, 0x31dc9c88, v142
	v_fmac_f32_e32 v151, 0x31dc9c88, v143
	v_sin_f32_e32 v140, v145
	v_cos_f32_e32 v142, v145
	v_sin_f32_e32 v141, v149
	v_cos_f32_e32 v143, v149
	v_mul_f32_e32 v144, v129, v157
	v_mul_f32_e32 v152, 0.15915494, v144
	v_rndne_f32_e32 v152, v152
	v_fma_f32 v158, v144, 0.15915494, -v152
	v_pk_mul_f32 v[152:153], v[124:125], v[140:141]
	v_pk_mul_f32 v[124:125], v[124:125], v[142:143]
	v_pk_fma_f32 v[142:143], v[120:121], v[142:143], v[152:153] neg_lo:[0,0,1] neg_hi:[0,0,1]
	v_pk_fma_f32 v[120:121], v[120:121], v[140:141], v[124:125]
	v_pk_mul_f32 v[140:141], v[128:129], v[142:143] op_sel_hi:[0,1]
	v_pk_mul_f32 v[142:143], v[128:129], v[120:121] op_sel_hi:[0,1]
	v_or_b32_e32 v120, 5, v156
	v_cvt_f32_ubyte0_e32 v120, v120
	v_mul_f32_e32 v121, 0xbed49a78, v120
	v_cmp_gt_f32_e32 vcc, s42, v121
	v_fmac_f32_e32 v158, 0x31dc9c88, v144
	v_sin_f32_e32 v144, v150
	v_cndmask_b32_e32 v121, 0, v147, vcc
	v_fmac_f32_e32 v121, 0xbed49a78, v120
	v_exp_f32_e32 v120, v121
	v_cndmask_b32_e32 v121, 0, v148, vcc
	v_cos_f32_e32 v150, v150
	v_sin_f32_e32 v145, v151
	v_ldexp_f32 v120, v120, v121
	v_mul_f32_e32 v121, v120, v157
	v_cos_f32_e32 v151, v151
	v_mul_f32_e32 v149, 0.15915494, v121
	v_rndne_f32_e32 v149, v149
	v_fma_f32 v149, v121, 0.15915494, -v149
	v_fmac_f32_e32 v149, 0x31dc9c88, v121
	v_or_b32_e32 v121, 6, v156
	v_pk_mul_f32 v[154:155], v[126:127], v[144:145]
	v_pk_mul_f32 v[126:127], v[126:127], v[150:151]
	v_cvt_f32_ubyte0_e32 v121, v121
	v_pk_fma_f32 v[124:125], v[122:123], v[150:151], v[154:155] neg_lo:[0,0,1] neg_hi:[0,0,1]
	v_pk_fma_f32 v[122:123], v[122:123], v[144:145], v[126:127]
	v_mul_f32_e32 v144, 0xbed49a78, v121
	v_cmp_gt_f32_e32 vcc, s42, v144
	v_sin_f32_e32 v150, v158
	v_cos_f32_e32 v152, v158
	v_cndmask_b32_e32 v144, 0, v147, vcc
	v_sin_f32_e32 v151, v149
	v_cos_f32_e32 v153, v149
	v_fmac_f32_e32 v144, 0xbed49a78, v121
	v_exp_f32_e32 v121, v144
	v_pk_mul_f32 v[126:127], v[112:113], v[150:151]
	v_pk_mul_f32 v[144:145], v[112:113], v[152:153]
	v_cndmask_b32_e32 v112, 0, v148, vcc
	v_ldexp_f32 v112, v121, v112
	v_mul_f32_e32 v113, v112, v157
	v_mul_f32_e32 v121, 0.15915494, v113
	v_rndne_f32_e32 v121, v121
	v_fma_f32 v121, v113, 0.15915494, -v121
	v_fmac_f32_e32 v121, 0x31dc9c88, v113
	v_or_b32_e32 v113, 7, v156
	v_cvt_f32_ubyte0_e32 v113, v113
	v_mul_f32_e32 v149, 0xbed49a78, v113
	v_cmp_gt_f32_e32 vcc, s42, v149
	v_pk_fma_f32 v[126:127], v[116:117], v[152:153], v[126:127] neg_lo:[0,0,1] neg_hi:[0,0,1]
	v_sin_f32_e32 v152, v121
	v_cndmask_b32_e32 v149, 0, v147, vcc
	v_fmac_f32_e32 v149, 0xbed49a78, v113
	v_exp_f32_e32 v113, v149
	v_cos_f32_e32 v154, v121
	v_cndmask_b32_e32 v121, 0, v148, vcc
	v_pk_fma_f32 v[116:117], v[116:117], v[150:151], v[144:145]
	v_ldexp_f32 v113, v113, v121
	v_mul_f32_e32 v121, v113, v157
	v_mul_f32_e32 v149, 0.15915494, v121
	v_rndne_f32_e32 v149, v149
	v_fma_f32 v149, v121, 0.15915494, -v149
	v_fmac_f32_e32 v149, 0x31dc9c88, v121
	v_sin_f32_e32 v153, v149
	v_cos_f32_e32 v155, v149
	v_pk_mul_f32 v[144:145], v[128:129], v[116:117] op_sel_hi:[0,1]
	v_pk_mul_f32 v[124:125], v[128:129], v[124:125] op_sel_hi:[0,1]
	v_pk_mul_f32 v[116:117], v[114:115], v[152:153]
	v_pk_mul_f32 v[114:115], v[114:115], v[154:155]
	v_pk_fma_f32 v[116:117], v[118:119], v[154:155], v[116:117] neg_lo:[0,0,1] neg_hi:[0,0,1]
	v_pk_mul_f32 v[126:127], v[128:129], v[126:127] op_sel_hi:[0,1]
	v_pk_mul_f32 v[150:151], v[128:129], v[116:117] op_sel_hi:[0,1]
	v_pk_fma_f32 v[114:115], v[118:119], v[152:153], v[114:115]
	v_pk_mul_f32 v[122:123], v[128:129], v[122:123] op_sel_hi:[0,1]
	v_pk_mul_f32 v[118:119], v[128:129], v[114:115] op_sel_hi:[0,1]
	v_mad_i64_i32 v[152:153], s[2:3], v138, s40, v[132:133]
	v_cvt_pk_bf16_f32 v114, v140, v141
	v_cvt_pk_bf16_f32 v115, v124, v125
	v_cvt_pk_bf16_f32 v116, v126, v127
	v_cvt_pk_bf16_f32 v117, v150, v151
	global_store_dwordx4 v[152:153], v[114:117], off
	v_or_b32_e32 v124, 16, v138
	s_nop 0
	v_cvt_pk_bf16_f32 v114, v142, v143
	v_cvt_pk_bf16_f32 v115, v122, v123
	v_cvt_pk_bf16_f32 v116, v144, v145
	v_cvt_pk_bf16_f32 v117, v118, v119
	global_store_dwordx4 v[152:153], v[114:117], off offset:64
	s_nop 1
	v_mov_b32_e32 v114, v242
	v_cvt_f32_i32_e32 v121, v114
	v_mul_f32_e32 v114, v139, v121
	v_mul_f32_e32 v115, v136, v121
	v_mul_f32_e32 v116, 0.15915494, v114
	v_mul_f32_e32 v117, 0.15915494, v115
	v_rndne_f32_e32 v116, v116
	v_rndne_f32_e32 v117, v117
	v_fma_f32 v116, v114, 0.15915494, -v116
	v_fma_f32 v117, v115, 0.15915494, -v117
	v_fmac_f32_e32 v116, 0x31dc9c88, v114
	v_fmac_f32_e32 v117, 0x31dc9c88, v115
	v_sin_f32_e32 v114, v116
	v_sin_f32_e32 v115, v117
	v_cos_f32_e32 v116, v116
	v_cos_f32_e32 v117, v117
	v_mul_f32_e32 v122, v135, v121
	v_pk_mul_f32 v[118:119], v[108:109], v[114:115]
	v_pk_mul_f32 v[108:109], v[108:109], v[116:117]
	v_pk_fma_f32 v[116:117], v[104:105], v[116:117], v[118:119] neg_lo:[0,0,1] neg_hi:[0,0,1]
	v_mul_f32_e32 v118, 0.15915494, v122
	v_rndne_f32_e32 v118, v118
	v_fma_f32 v119, v122, 0.15915494, -v118
	v_fmac_f32_e32 v119, 0x31dc9c88, v122
	v_sin_f32_e32 v118, v119
	v_cos_f32_e32 v122, v119
	v_mul_f32_e32 v119, v134, v121
	v_mul_f32_e32 v123, 0.15915494, v119
	v_rndne_f32_e32 v123, v123
	v_fma_f32 v123, v119, 0.15915494, -v123
	v_fmac_f32_e32 v123, 0x31dc9c88, v119
	v_sin_f32_e32 v119, v123
	v_pk_fma_f32 v[104:105], v[104:105], v[114:115], v[108:109]
	v_mul_f32_e32 v114, v129, v121
	v_cos_f32_e32 v123, v123
	v_mul_f32_e32 v115, 0.15915494, v114
	v_rndne_f32_e32 v115, v115
	v_fma_f32 v115, v114, 0.15915494, -v115
	v_pk_mul_f32 v[108:109], v[110:111], v[118:119]
	v_fmac_f32_e32 v115, 0x31dc9c88, v114
	v_pk_fma_f32 v[108:109], v[106:107], v[122:123], v[108:109] neg_lo:[0,0,1] neg_hi:[0,0,1]
	v_pk_mul_f32 v[110:111], v[110:111], v[122:123]
	v_sin_f32_e32 v114, v115
	v_cos_f32_e32 v122, v115
	v_mul_f32_e32 v115, v120, v121
	v_mul_f32_e32 v123, 0.15915494, v115
	v_rndne_f32_e32 v123, v123
	v_fma_f32 v123, v115, 0.15915494, -v123
	v_fmac_f32_e32 v123, 0x31dc9c88, v115
	v_sin_f32_e32 v115, v123
	v_pk_fma_f32 v[106:107], v[106:107], v[118:119], v[110:111]
	v_mul_f32_e32 v118, v112, v121
	v_cos_f32_e32 v123, v123
	v_mul_f32_e32 v119, 0.15915494, v118
	v_rndne_f32_e32 v119, v119
	v_fma_f32 v119, v118, 0.15915494, -v119
	v_pk_mul_f32 v[110:111], v[96:97], v[114:115]
	v_fmac_f32_e32 v119, 0x31dc9c88, v118
	v_pk_fma_f32 v[110:111], v[100:101], v[122:123], v[110:111] neg_lo:[0,0,1] neg_hi:[0,0,1]
	v_pk_mul_f32 v[96:97], v[96:97], v[122:123]
	v_sin_f32_e32 v118, v119
	v_cos_f32_e32 v122, v119
	v_mul_f32_e32 v119, v113, v121
	v_mul_f32_e32 v121, 0.15915494, v119
	v_rndne_f32_e32 v121, v121
	v_fma_f32 v121, v119, 0.15915494, -v121
	v_fmac_f32_e32 v121, 0x31dc9c88, v119
	v_sin_f32_e32 v119, v121
	v_cos_f32_e32 v123, v121
	v_pk_fma_f32 v[96:97], v[100:101], v[114:115], v[96:97]
	v_pk_mul_f32 v[116:117], v[128:129], v[116:117] op_sel_hi:[0,1]
	v_pk_mul_f32 v[100:101], v[128:129], v[96:97] op_sel_hi:[0,1]
	v_pk_mul_f32 v[96:97], v[98:99], v[118:119]
	v_pk_mul_f32 v[108:109], v[128:129], v[108:109] op_sel_hi:[0,1]
	v_pk_fma_f32 v[96:97], v[102:103], v[122:123], v[96:97] neg_lo:[0,0,1] neg_hi:[0,0,1]
	v_pk_mul_f32 v[110:111], v[128:129], v[110:111] op_sel_hi:[0,1]
	v_pk_mul_f32 v[114:115], v[128:129], v[96:97] op_sel_hi:[0,1]
	v_pk_mul_f32 v[96:97], v[98:99], v[122:123]
	v_pk_mul_f32 v[104:105], v[128:129], v[104:105] op_sel_hi:[0,1]
	v_pk_fma_f32 v[96:97], v[102:103], v[118:119], v[96:97]
	v_pk_mul_f32 v[106:107], v[128:129], v[106:107] op_sel_hi:[0,1]
	v_pk_mul_f32 v[102:103], v[128:129], v[96:97] op_sel_hi:[0,1]
	v_mad_i64_i32 v[118:119], s[2:3], v124, s40, v[132:133]
	v_cvt_pk_bf16_f32 v96, v116, v117
	v_cvt_pk_bf16_f32 v97, v108, v109
	v_cvt_pk_bf16_f32 v98, v110, v111
	v_cvt_pk_bf16_f32 v99, v114, v115
	global_store_dwordx4 v[118:119], v[96:99], off
	s_nop 1
	v_cvt_pk_bf16_f32 v96, v104, v105
	v_cvt_pk_bf16_f32 v97, v106, v107
	v_cvt_pk_bf16_f32 v98, v100, v101
	v_cvt_pk_bf16_f32 v99, v102, v103
	global_store_dwordx4 v[118:119], v[96:99], off offset:64
	s_nop 1
	v_mov_b32_e32 v96, v243
	v_or_b32_e32 v105, 32, v138
	v_cvt_f32_i32_e32 v104, v96
	v_mul_f32_e32 v96, v139, v104
	v_mul_f32_e32 v97, v136, v104
	v_mul_f32_e32 v98, 0.15915494, v96
	v_mul_f32_e32 v99, 0.15915494, v97
	v_rndne_f32_e32 v98, v98
	v_rndne_f32_e32 v99, v99
	v_fma_f32 v98, v96, 0.15915494, -v98
	v_fma_f32 v99, v97, 0.15915494, -v99
	v_fmac_f32_e32 v98, 0x31dc9c88, v96
	v_fmac_f32_e32 v99, 0x31dc9c88, v97
	v_sin_f32_e32 v96, v98
	v_sin_f32_e32 v97, v99
	v_mul_f32_e32 v102, v135, v104
	v_cos_f32_e32 v98, v98
	v_cos_f32_e32 v99, v99
	v_mul_f32_e32 v100, 0.15915494, v102
	v_rndne_f32_e32 v100, v100
	v_fma_f32 v103, v102, 0.15915494, -v100
	v_pk_mul_f32 v[100:101], v[92:93], v[96:97]
	v_pk_mul_f32 v[92:93], v[92:93], v[98:99]
	v_pk_fma_f32 v[98:99], v[88:89], v[98:99], v[100:101] neg_lo:[0,0,1] neg_hi:[0,0,1]
	v_fmac_f32_e32 v103, 0x31dc9c88, v102
	v_mul_f32_e32 v101, v134, v104
	v_sin_f32_e32 v100, v103
	v_cos_f32_e32 v102, v103
	v_mul_f32_e32 v103, 0.15915494, v101
	v_rndne_f32_e32 v103, v103
	v_fma_f32 v103, v101, 0.15915494, -v103
	v_fmac_f32_e32 v103, 0x31dc9c88, v101
	v_sin_f32_e32 v101, v103
	v_pk_fma_f32 v[88:89], v[88:89], v[96:97], v[92:93]
	v_mul_f32_e32 v96, v129, v104
	v_cos_f32_e32 v103, v103
	v_mul_f32_e32 v97, 0.15915494, v96
	v_rndne_f32_e32 v97, v97
	v_fma_f32 v97, v96, 0.15915494, -v97
	v_pk_mul_f32 v[92:93], v[94:95], v[100:101]
	v_fmac_f32_e32 v97, 0x31dc9c88, v96
	v_pk_fma_f32 v[92:93], v[90:91], v[102:103], v[92:93] neg_lo:[0,0,1] neg_hi:[0,0,1]
	v_pk_mul_f32 v[94:95], v[94:95], v[102:103]
	v_sin_f32_e32 v96, v97
	v_cos_f32_e32 v102, v97
	v_mul_f32_e32 v97, v120, v104
	v_mul_f32_e32 v103, 0.15915494, v97
	v_rndne_f32_e32 v103, v103
	v_fma_f32 v103, v97, 0.15915494, -v103
	v_fmac_f32_e32 v103, 0x31dc9c88, v97
	v_sin_f32_e32 v97, v103
	v_pk_fma_f32 v[90:91], v[90:91], v[100:101], v[94:95]
	v_mul_f32_e32 v100, v112, v104
	v_cos_f32_e32 v103, v103
	v_mul_f32_e32 v101, 0.15915494, v100
	v_rndne_f32_e32 v101, v101
	v_fma_f32 v101, v100, 0.15915494, -v101
	v_pk_mul_f32 v[94:95], v[80:81], v[96:97]
	v_fmac_f32_e32 v101, 0x31dc9c88, v100
	v_pk_fma_f32 v[94:95], v[84:85], v[102:103], v[94:95] neg_lo:[0,0,1] neg_hi:[0,0,1]
	v_pk_mul_f32 v[80:81], v[80:81], v[102:103]
	v_sin_f32_e32 v100, v101
	v_cos_f32_e32 v102, v101
	v_mul_f32_e32 v101, v113, v104
	v_mul_f32_e32 v103, 0.15915494, v101
	v_rndne_f32_e32 v103, v103
	v_fma_f32 v103, v101, 0.15915494, -v103
	v_fmac_f32_e32 v103, 0x31dc9c88, v101
	v_sin_f32_e32 v101, v103
	v_cos_f32_e32 v103, v103
	v_pk_fma_f32 v[80:81], v[84:85], v[96:97], v[80:81]
	v_pk_mul_f32 v[98:99], v[128:129], v[98:99] op_sel_hi:[0,1]
	v_pk_mul_f32 v[84:85], v[128:129], v[80:81] op_sel_hi:[0,1]
	v_pk_mul_f32 v[80:81], v[82:83], v[100:101]
	v_pk_mul_f32 v[92:93], v[128:129], v[92:93] op_sel_hi:[0,1]
	v_pk_fma_f32 v[80:81], v[86:87], v[102:103], v[80:81] neg_lo:[0,0,1] neg_hi:[0,0,1]
	v_pk_mul_f32 v[94:95], v[128:129], v[94:95] op_sel_hi:[0,1]
	v_pk_mul_f32 v[96:97], v[128:129], v[80:81] op_sel_hi:[0,1]
	v_pk_mul_f32 v[80:81], v[82:83], v[102:103]
	v_pk_mul_f32 v[88:89], v[128:129], v[88:89] op_sel_hi:[0,1]
	v_pk_fma_f32 v[80:81], v[86:87], v[100:101], v[80:81]
	v_pk_mul_f32 v[90:91], v[128:129], v[90:91] op_sel_hi:[0,1]
	v_pk_mul_f32 v[86:87], v[128:129], v[80:81] op_sel_hi:[0,1]
	v_mad_i64_i32 v[100:101], s[2:3], v105, s40, v[132:133]
	v_cvt_pk_bf16_f32 v80, v98, v99
	v_cvt_pk_bf16_f32 v81, v92, v93
	v_cvt_pk_bf16_f32 v82, v94, v95
	v_cvt_pk_bf16_f32 v83, v96, v97
	global_store_dwordx4 v[100:101], v[80:83], off
	s_nop 1
	v_cvt_pk_bf16_f32 v80, v88, v89
	v_cvt_pk_bf16_f32 v81, v90, v91
	v_cvt_pk_bf16_f32 v82, v84, v85
	v_cvt_pk_bf16_f32 v83, v86, v87
	global_store_dwordx4 v[100:101], v[80:83], off offset:64
	s_nop 1
	v_mov_b32_e32 v80, v244
	v_or_b32_e32 v91, 48, v138
	v_cvt_f32_i32_e32 v90, v80
	v_mul_f32_e32 v80, v139, v90
	v_mul_f32_e32 v81, v136, v90
	v_mul_f32_e32 v82, v135, v90
	v_mul_f32_e32 v83, 0.15915494, v80
	v_mul_f32_e32 v84, 0.15915494, v81
	v_mul_f32_e32 v85, 0.15915494, v82
	v_rndne_f32_e32 v83, v83
	v_rndne_f32_e32 v84, v84
	v_rndne_f32_e32 v85, v85
	v_fma_f32 v83, v80, 0.15915494, -v83
	v_fma_f32 v84, v81, 0.15915494, -v84
	v_fma_f32 v85, v82, 0.15915494, -v85
	v_fmac_f32_e32 v83, 0x31dc9c88, v80
	v_fmac_f32_e32 v84, 0x31dc9c88, v81
	v_fmac_f32_e32 v85, 0x31dc9c88, v82
	v_sin_f32_e32 v80, v83
	v_cos_f32_e32 v82, v83
	v_sin_f32_e32 v81, v84
	v_cos_f32_e32 v83, v84
	v_sin_f32_e32 v84, v85
	v_cos_f32_e32 v86, v85
	v_mul_f32_e32 v85, v134, v90
	v_mul_f32_e32 v87, 0.15915494, v85
	v_rndne_f32_e32 v87, v87
	v_fma_f32 v87, v85, 0.15915494, -v87
	v_pk_mul_f32 v[88:89], v[76:77], v[80:81]
	v_pk_mul_f32 v[76:77], v[76:77], v[82:83]
	v_fmac_f32_e32 v87, 0x31dc9c88, v85
	v_pk_fma_f32 v[82:83], v[72:73], v[82:83], v[88:89] neg_lo:[0,0,1] neg_hi:[0,0,1]
	v_sin_f32_e32 v85, v87
	v_pk_fma_f32 v[72:73], v[72:73], v[80:81], v[76:77]
	v_mul_f32_e32 v80, v129, v90
	v_cos_f32_e32 v87, v87
	v_mul_f32_e32 v81, 0.15915494, v80
	v_rndne_f32_e32 v81, v81
	v_fma_f32 v81, v80, 0.15915494, -v81
	v_pk_mul_f32 v[76:77], v[78:79], v[84:85]
	v_fmac_f32_e32 v81, 0x31dc9c88, v80
	v_pk_fma_f32 v[76:77], v[74:75], v[86:87], v[76:77] neg_lo:[0,0,1] neg_hi:[0,0,1]
	v_pk_mul_f32 v[78:79], v[78:79], v[86:87]
	v_sin_f32_e32 v80, v81
	v_cos_f32_e32 v86, v81
	v_mul_f32_e32 v81, v120, v90
	v_mul_f32_e32 v87, 0.15915494, v81
	v_rndne_f32_e32 v87, v87
	v_fma_f32 v87, v81, 0.15915494, -v87
	v_fmac_f32_e32 v87, 0x31dc9c88, v81
	v_sin_f32_e32 v81, v87
	v_pk_fma_f32 v[74:75], v[74:75], v[84:85], v[78:79]
	v_mul_f32_e32 v84, v112, v90
	v_cos_f32_e32 v87, v87
	v_mul_f32_e32 v85, 0.15915494, v84
	v_rndne_f32_e32 v85, v85
	v_fma_f32 v85, v84, 0.15915494, -v85
	v_pk_mul_f32 v[78:79], v[64:65], v[80:81]
	v_fmac_f32_e32 v85, 0x31dc9c88, v84
	v_pk_fma_f32 v[78:79], v[68:69], v[86:87], v[78:79] neg_lo:[0,0,1] neg_hi:[0,0,1]
	v_pk_mul_f32 v[64:65], v[64:65], v[86:87]
	v_sin_f32_e32 v84, v85
	v_cos_f32_e32 v86, v85
	v_mul_f32_e32 v85, v113, v90
	v_mul_f32_e32 v87, 0.15915494, v85
	v_rndne_f32_e32 v87, v87
	v_fma_f32 v87, v85, 0.15915494, -v87
	v_fmac_f32_e32 v87, 0x31dc9c88, v85
	v_sin_f32_e32 v85, v87
	v_cos_f32_e32 v87, v87
	v_pk_fma_f32 v[64:65], v[68:69], v[80:81], v[64:65]
	v_pk_mul_f32 v[82:83], v[128:129], v[82:83] op_sel_hi:[0,1]
	v_pk_mul_f32 v[68:69], v[128:129], v[64:65] op_sel_hi:[0,1]
	v_pk_mul_f32 v[64:65], v[66:67], v[84:85]
	v_pk_mul_f32 v[76:77], v[128:129], v[76:77] op_sel_hi:[0,1]
	v_pk_fma_f32 v[64:65], v[70:71], v[86:87], v[64:65] neg_lo:[0,0,1] neg_hi:[0,0,1]
	v_pk_mul_f32 v[78:79], v[128:129], v[78:79] op_sel_hi:[0,1]
	v_pk_mul_f32 v[80:81], v[128:129], v[64:65] op_sel_hi:[0,1]
	v_pk_mul_f32 v[64:65], v[66:67], v[86:87]
	v_pk_mul_f32 v[72:73], v[128:129], v[72:73] op_sel_hi:[0,1]
	v_pk_fma_f32 v[64:65], v[70:71], v[84:85], v[64:65]
	v_pk_mul_f32 v[74:75], v[128:129], v[74:75] op_sel_hi:[0,1]
	v_pk_mul_f32 v[70:71], v[128:129], v[64:65] op_sel_hi:[0,1]
	v_mad_i64_i32 v[84:85], s[2:3], v91, s40, v[132:133]
	v_cvt_pk_bf16_f32 v64, v82, v83
	v_cvt_pk_bf16_f32 v65, v76, v77
	v_cvt_pk_bf16_f32 v66, v78, v79
	v_cvt_pk_bf16_f32 v67, v80, v81
	global_store_dwordx4 v[84:85], v[64:67], off
	s_nop 1
	v_cvt_pk_bf16_f32 v64, v72, v73
	v_cvt_pk_bf16_f32 v65, v74, v75
	v_cvt_pk_bf16_f32 v66, v68, v69
	v_cvt_pk_bf16_f32 v67, v70, v71
	global_store_dwordx4 v[84:85], v[64:67], off offset:64
	s_nop 1
	v_mov_b32_e32 v64, v245
	v_or_b32_e32 v75, 64, v138
	v_cvt_f32_i32_e32 v74, v64
	v_mul_f32_e32 v64, v139, v74
	v_mul_f32_e32 v65, v136, v74
	v_mul_f32_e32 v66, v135, v74
	v_mul_f32_e32 v67, 0.15915494, v64
	v_mul_f32_e32 v68, 0.15915494, v65
	v_mul_f32_e32 v70, 0.15915494, v66
	v_rndne_f32_e32 v67, v67
	v_rndne_f32_e32 v68, v68
	v_rndne_f32_e32 v70, v70
	v_fma_f32 v67, v64, 0.15915494, -v67
	v_fma_f32 v68, v65, 0.15915494, -v68
	v_fma_f32 v70, v66, 0.15915494, -v70
	v_fmac_f32_e32 v67, 0x31dc9c88, v64
	v_fmac_f32_e32 v68, 0x31dc9c88, v65
	v_mul_f32_e32 v69, v134, v74
	v_fmac_f32_e32 v70, 0x31dc9c88, v66
	v_sin_f32_e32 v64, v67
	v_cos_f32_e32 v66, v67
	v_sin_f32_e32 v65, v68
	v_cos_f32_e32 v67, v68
	v_mul_f32_e32 v71, 0.15915494, v69
	v_rndne_f32_e32 v71, v71
	v_fma_f32 v71, v69, 0.15915494, -v71
	v_pk_mul_f32 v[72:73], v[60:61], v[64:65]
	v_pk_mul_f32 v[60:61], v[60:61], v[66:67]
	v_fmac_f32_e32 v71, 0x31dc9c88, v69
	v_sin_f32_e32 v68, v70
	v_pk_fma_f32 v[66:67], v[56:57], v[66:67], v[72:73] neg_lo:[0,0,1] neg_hi:[0,0,1]
	v_sin_f32_e32 v69, v71
	v_pk_fma_f32 v[56:57], v[56:57], v[64:65], v[60:61]
	v_mul_f32_e32 v64, v129, v74
	v_cos_f32_e32 v70, v70
	v_cos_f32_e32 v71, v71
	v_mul_f32_e32 v65, 0.15915494, v64
	v_rndne_f32_e32 v65, v65
	v_fma_f32 v65, v64, 0.15915494, -v65
	v_pk_mul_f32 v[60:61], v[62:63], v[68:69]
	v_fmac_f32_e32 v65, 0x31dc9c88, v64
	v_pk_fma_f32 v[60:61], v[58:59], v[70:71], v[60:61] neg_lo:[0,0,1] neg_hi:[0,0,1]
	v_pk_mul_f32 v[62:63], v[62:63], v[70:71]
	v_sin_f32_e32 v64, v65
	v_cos_f32_e32 v70, v65
	v_mul_f32_e32 v65, v120, v74
	v_mul_f32_e32 v71, 0.15915494, v65
	v_rndne_f32_e32 v71, v71
	v_fma_f32 v71, v65, 0.15915494, -v71
	v_fmac_f32_e32 v71, 0x31dc9c88, v65
	v_sin_f32_e32 v65, v71
	v_pk_fma_f32 v[58:59], v[58:59], v[68:69], v[62:63]
	v_mul_f32_e32 v68, v112, v74
	v_cos_f32_e32 v71, v71
	v_mul_f32_e32 v69, 0.15915494, v68
	v_rndne_f32_e32 v69, v69
	v_fma_f32 v69, v68, 0.15915494, -v69
	v_pk_mul_f32 v[62:63], v[48:49], v[64:65]
	v_fmac_f32_e32 v69, 0x31dc9c88, v68
	v_pk_fma_f32 v[62:63], v[52:53], v[70:71], v[62:63] neg_lo:[0,0,1] neg_hi:[0,0,1]
	v_pk_mul_f32 v[48:49], v[48:49], v[70:71]
	v_sin_f32_e32 v68, v69
	v_cos_f32_e32 v70, v69
	v_mul_f32_e32 v69, v113, v74
	v_mul_f32_e32 v71, 0.15915494, v69
	v_rndne_f32_e32 v71, v71
	v_fma_f32 v71, v69, 0.15915494, -v71
	v_fmac_f32_e32 v71, 0x31dc9c88, v69
	v_sin_f32_e32 v69, v71
	v_cos_f32_e32 v71, v71
	v_pk_fma_f32 v[48:49], v[52:53], v[64:65], v[48:49]
	v_pk_mul_f32 v[66:67], v[128:129], v[66:67] op_sel_hi:[0,1]
	v_pk_mul_f32 v[52:53], v[128:129], v[48:49] op_sel_hi:[0,1]
	v_pk_mul_f32 v[48:49], v[50:51], v[68:69]
	v_pk_mul_f32 v[60:61], v[128:129], v[60:61] op_sel_hi:[0,1]
	v_pk_fma_f32 v[48:49], v[54:55], v[70:71], v[48:49] neg_lo:[0,0,1] neg_hi:[0,0,1]
	v_pk_mul_f32 v[62:63], v[128:129], v[62:63] op_sel_hi:[0,1]
	v_pk_mul_f32 v[64:65], v[128:129], v[48:49] op_sel_hi:[0,1]
	v_pk_mul_f32 v[48:49], v[50:51], v[70:71]
	v_pk_mul_f32 v[56:57], v[128:129], v[56:57] op_sel_hi:[0,1]
	v_pk_fma_f32 v[48:49], v[54:55], v[68:69], v[48:49]
	v_pk_mul_f32 v[58:59], v[128:129], v[58:59] op_sel_hi:[0,1]
	v_pk_mul_f32 v[54:55], v[128:129], v[48:49] op_sel_hi:[0,1]
	v_mad_i64_i32 v[68:69], s[2:3], v75, s40, v[132:133]
	v_cvt_pk_bf16_f32 v48, v66, v67
	v_cvt_pk_bf16_f32 v49, v60, v61
	v_cvt_pk_bf16_f32 v50, v62, v63
	v_cvt_pk_bf16_f32 v51, v64, v65
	global_store_dwordx4 v[68:69], v[48:51], off
	s_nop 1
	v_cvt_pk_bf16_f32 v48, v56, v57
	v_cvt_pk_bf16_f32 v49, v58, v59
	v_cvt_pk_bf16_f32 v50, v52, v53
	v_cvt_pk_bf16_f32 v51, v54, v55
	global_store_dwordx4 v[68:69], v[48:51], off offset:64
	s_nop 1
	v_mov_b32_e32 v48, v246
	v_or_b32_e32 v59, 0x50, v138
	v_cvt_f32_i32_e32 v58, v48
	v_mul_f32_e32 v48, v139, v58
	v_mul_f32_e32 v49, v136, v58
	v_mul_f32_e32 v50, v135, v58
	v_mul_f32_e32 v51, v134, v58
	v_mul_f32_e32 v52, 0.15915494, v48
	v_mul_f32_e32 v53, 0.15915494, v49
	v_mul_f32_e32 v54, 0.15915494, v50
	v_mul_f32_e32 v55, 0.15915494, v51
	v_rndne_f32_e32 v52, v52
	v_rndne_f32_e32 v53, v53
	v_rndne_f32_e32 v54, v54
	v_rndne_f32_e32 v55, v55
	v_fma_f32 v52, v48, 0.15915494, -v52
	v_fma_f32 v53, v49, 0.15915494, -v53
	v_fma_f32 v54, v50, 0.15915494, -v54
	v_fma_f32 v55, v51, 0.15915494, -v55
	v_fmac_f32_e32 v52, 0x31dc9c88, v48
	v_fmac_f32_e32 v53, 0x31dc9c88, v49
	v_fmac_f32_e32 v54, 0x31dc9c88, v50
	v_fmac_f32_e32 v55, 0x31dc9c88, v51
	v_sin_f32_e32 v48, v52
	v_cos_f32_e32 v50, v52
	v_sin_f32_e32 v49, v53
	v_cos_f32_e32 v51, v53
	v_sin_f32_e32 v52, v54
	v_sin_f32_e32 v53, v55
	v_pk_mul_f32 v[56:57], v[44:45], v[48:49]
	v_pk_mul_f32 v[44:45], v[44:45], v[50:51]
	v_pk_fma_f32 v[50:51], v[40:41], v[50:51], v[56:57] neg_lo:[0,0,1] neg_hi:[0,0,1]
	v_pk_fma_f32 v[40:41], v[40:41], v[48:49], v[44:45]
	v_mul_f32_e32 v48, v129, v58
	v_cos_f32_e32 v54, v54
	v_cos_f32_e32 v55, v55
	v_mul_f32_e32 v49, 0.15915494, v48
	v_rndne_f32_e32 v49, v49
	v_fma_f32 v49, v48, 0.15915494, -v49
	v_pk_mul_f32 v[44:45], v[46:47], v[52:53]
	v_fmac_f32_e32 v49, 0x31dc9c88, v48
	v_pk_fma_f32 v[44:45], v[42:43], v[54:55], v[44:45] neg_lo:[0,0,1] neg_hi:[0,0,1]
	v_pk_mul_f32 v[46:47], v[46:47], v[54:55]
	v_sin_f32_e32 v48, v49
	v_cos_f32_e32 v54, v49
	v_mul_f32_e32 v49, v120, v58
	v_mul_f32_e32 v55, 0.15915494, v49
	v_rndne_f32_e32 v55, v55
	v_fma_f32 v55, v49, 0.15915494, -v55
	v_fmac_f32_e32 v55, 0x31dc9c88, v49
	v_sin_f32_e32 v49, v55
	v_pk_fma_f32 v[42:43], v[42:43], v[52:53], v[46:47]
	v_mul_f32_e32 v52, v112, v58
	v_cos_f32_e32 v55, v55
	v_mul_f32_e32 v53, 0.15915494, v52
	v_rndne_f32_e32 v53, v53
	v_fma_f32 v53, v52, 0.15915494, -v53
	v_pk_mul_f32 v[46:47], v[32:33], v[48:49]
	v_fmac_f32_e32 v53, 0x31dc9c88, v52
	v_pk_fma_f32 v[46:47], v[36:37], v[54:55], v[46:47] neg_lo:[0,0,1] neg_hi:[0,0,1]
	v_pk_mul_f32 v[32:33], v[32:33], v[54:55]
	v_sin_f32_e32 v52, v53
	v_cos_f32_e32 v54, v53
	v_mul_f32_e32 v53, v113, v58
	v_mul_f32_e32 v55, 0.15915494, v53
	v_rndne_f32_e32 v55, v55
	v_fma_f32 v55, v53, 0.15915494, -v55
	v_fmac_f32_e32 v55, 0x31dc9c88, v53
	v_sin_f32_e32 v53, v55
	v_cos_f32_e32 v55, v55
	v_pk_fma_f32 v[32:33], v[36:37], v[48:49], v[32:33]
	v_pk_mul_f32 v[50:51], v[128:129], v[50:51] op_sel_hi:[0,1]
	v_pk_mul_f32 v[36:37], v[128:129], v[32:33] op_sel_hi:[0,1]
	v_pk_mul_f32 v[32:33], v[34:35], v[52:53]
	v_pk_mul_f32 v[44:45], v[128:129], v[44:45] op_sel_hi:[0,1]
	v_pk_fma_f32 v[32:33], v[38:39], v[54:55], v[32:33] neg_lo:[0,0,1] neg_hi:[0,0,1]
	v_pk_mul_f32 v[46:47], v[128:129], v[46:47] op_sel_hi:[0,1]
	v_pk_mul_f32 v[48:49], v[128:129], v[32:33] op_sel_hi:[0,1]
	v_pk_mul_f32 v[32:33], v[34:35], v[54:55]
	v_pk_mul_f32 v[40:41], v[128:129], v[40:41] op_sel_hi:[0,1]
	v_pk_fma_f32 v[32:33], v[38:39], v[52:53], v[32:33]
	v_pk_mul_f32 v[42:43], v[128:129], v[42:43] op_sel_hi:[0,1]
	v_pk_mul_f32 v[38:39], v[128:129], v[32:33] op_sel_hi:[0,1]
	v_mad_i64_i32 v[52:53], s[2:3], v59, s40, v[132:133]
	v_cvt_pk_bf16_f32 v32, v50, v51
	v_cvt_pk_bf16_f32 v33, v44, v45
	v_cvt_pk_bf16_f32 v34, v46, v47
	v_cvt_pk_bf16_f32 v35, v48, v49
	global_store_dwordx4 v[52:53], v[32:35], off
	s_nop 1
	v_cvt_pk_bf16_f32 v32, v40, v41
	v_cvt_pk_bf16_f32 v33, v42, v43
	v_cvt_pk_bf16_f32 v34, v36, v37
	v_cvt_pk_bf16_f32 v35, v38, v39
	global_store_dwordx4 v[52:53], v[32:35], off offset:64
	s_nop 1
	v_mov_b32_e32 v32, v247
	v_or_b32_e32 v43, 0x60, v138
	v_cvt_f32_i32_e32 v42, v32
	v_mul_f32_e32 v32, v139, v42
	v_mul_f32_e32 v33, v136, v42
	v_mul_f32_e32 v36, 0.15915494, v32
	v_mul_f32_e32 v37, 0.15915494, v33
	v_mul_f32_e32 v34, v135, v42
	v_mul_f32_e32 v35, v134, v42
	v_rndne_f32_e32 v36, v36
	v_rndne_f32_e32 v37, v37
	v_mul_f32_e32 v38, 0.15915494, v34
	v_mul_f32_e32 v39, 0.15915494, v35
	v_fma_f32 v36, v32, 0.15915494, -v36
	v_fma_f32 v37, v33, 0.15915494, -v37
	v_rndne_f32_e32 v38, v38
	v_rndne_f32_e32 v39, v39
	v_fmac_f32_e32 v36, 0x31dc9c88, v32
	v_fmac_f32_e32 v37, 0x31dc9c88, v33
	v_fma_f32 v38, v34, 0.15915494, -v38
	v_fma_f32 v39, v35, 0.15915494, -v39
	v_sin_f32_e32 v32, v36
	v_sin_f32_e32 v33, v37
	v_fmac_f32_e32 v38, 0x31dc9c88, v34
	v_fmac_f32_e32 v39, 0x31dc9c88, v35
	v_cos_f32_e32 v34, v36
	v_cos_f32_e32 v35, v37
	v_pk_mul_f32 v[40:41], v[28:29], v[32:33]
	v_sin_f32_e32 v36, v38
	v_sin_f32_e32 v37, v39
	v_pk_mul_f32 v[28:29], v[28:29], v[34:35]
	v_pk_fma_f32 v[34:35], v[24:25], v[34:35], v[40:41] neg_lo:[0,0,1] neg_hi:[0,0,1]
	v_pk_fma_f32 v[24:25], v[24:25], v[32:33], v[28:29]
	v_pk_mul_f32 v[28:29], v[128:129], v[34:35] op_sel_hi:[0,1]
	v_mul_f32_e32 v34, v129, v42
	v_cos_f32_e32 v38, v38
	v_cos_f32_e32 v39, v39
	v_mul_f32_e32 v35, 0.15915494, v34
	v_rndne_f32_e32 v35, v35
	v_fma_f32 v35, v34, 0.15915494, -v35
	v_pk_mul_f32 v[32:33], v[30:31], v[36:37]
	v_fmac_f32_e32 v35, 0x31dc9c88, v34
	v_pk_fma_f32 v[32:33], v[26:27], v[38:39], v[32:33] neg_lo:[0,0,1] neg_hi:[0,0,1]
	v_pk_mul_f32 v[30:31], v[30:31], v[38:39]
	v_sin_f32_e32 v34, v35
	v_cos_f32_e32 v38, v35
	v_mul_f32_e32 v35, v120, v42
	v_mul_f32_e32 v39, 0.15915494, v35
	v_rndne_f32_e32 v39, v39
	v_fma_f32 v39, v35, 0.15915494, -v39
	v_fmac_f32_e32 v39, 0x31dc9c88, v35
	v_sin_f32_e32 v35, v39
	v_pk_fma_f32 v[26:27], v[26:27], v[36:37], v[30:31]
	v_mul_f32_e32 v36, v112, v42
	v_cos_f32_e32 v39, v39
	v_mul_f32_e32 v37, 0.15915494, v36
	v_rndne_f32_e32 v37, v37
	v_fma_f32 v37, v36, 0.15915494, -v37
	v_pk_mul_f32 v[30:31], v[16:17], v[34:35]
	v_fmac_f32_e32 v37, 0x31dc9c88, v36
	v_pk_fma_f32 v[30:31], v[20:21], v[38:39], v[30:31] neg_lo:[0,0,1] neg_hi:[0,0,1]
	v_pk_mul_f32 v[16:17], v[16:17], v[38:39]
	v_sin_f32_e32 v36, v37
	v_cos_f32_e32 v38, v37
	v_mul_f32_e32 v37, v113, v42
	v_mul_f32_e32 v39, 0.15915494, v37
	v_rndne_f32_e32 v39, v39
	v_fma_f32 v39, v37, 0.15915494, -v39
	v_fmac_f32_e32 v39, 0x31dc9c88, v37
	v_sin_f32_e32 v37, v39
	v_cos_f32_e32 v39, v39
	v_pk_fma_f32 v[16:17], v[20:21], v[34:35], v[16:17]
	v_pk_mul_f32 v[32:33], v[128:129], v[32:33] op_sel_hi:[0,1]
	v_pk_mul_f32 v[20:21], v[128:129], v[16:17] op_sel_hi:[0,1]
	v_pk_mul_f32 v[16:17], v[18:19], v[36:37]
	v_pk_mul_f32 v[30:31], v[128:129], v[30:31] op_sel_hi:[0,1]
	v_pk_fma_f32 v[16:17], v[22:23], v[38:39], v[16:17] neg_lo:[0,0,1] neg_hi:[0,0,1]
	v_pk_mul_f32 v[24:25], v[128:129], v[24:25] op_sel_hi:[0,1]
	v_pk_mul_f32 v[34:35], v[128:129], v[16:17] op_sel_hi:[0,1]
	v_pk_mul_f32 v[16:17], v[18:19], v[38:39]
	v_pk_mul_f32 v[26:27], v[128:129], v[26:27] op_sel_hi:[0,1]
	v_pk_fma_f32 v[16:17], v[22:23], v[36:37], v[16:17]
	v_mad_i64_i32 v[36:37], s[2:3], v43, s40, v[132:133]
	v_pk_mul_f32 v[22:23], v[128:129], v[16:17] op_sel_hi:[0,1]
	v_cvt_pk_bf16_f32 v16, v28, v29
	v_cvt_pk_bf16_f32 v17, v32, v33
	v_cvt_pk_bf16_f32 v18, v30, v31
	v_cvt_pk_bf16_f32 v19, v34, v35
	global_store_dwordx4 v[36:37], v[16:19], off
	v_or_b32_e32 v29, 0x70, v138
	v_mad_i64_i32 v[142:143], s[2:3], v29, s40, v[132:133]
	v_cvt_pk_bf16_f32 v16, v24, v25
	v_cvt_pk_bf16_f32 v17, v26, v27
	v_cvt_pk_bf16_f32 v18, v20, v21
	v_cvt_pk_bf16_f32 v19, v22, v23
	global_store_dwordx4 v[36:37], v[16:19], off offset:64
	s_nop 1
	v_mov_b32_e32 v16, v248
	v_cvt_f32_i32_e32 v28, v16
	v_mul_f32_e32 v16, v139, v28
	v_mul_f32_e32 v17, v136, v28
	v_mul_f32_e32 v20, 0.15915494, v16
	v_mul_f32_e32 v21, 0.15915494, v17
	v_mul_f32_e32 v18, v135, v28
	v_mul_f32_e32 v19, v134, v28
	v_rndne_f32_e32 v20, v20
	v_rndne_f32_e32 v21, v21
	v_mul_f32_e32 v22, 0.15915494, v18
	v_mul_f32_e32 v23, 0.15915494, v19
	v_fma_f32 v20, v16, 0.15915494, -v20
	v_fma_f32 v21, v17, 0.15915494, -v21
	v_rndne_f32_e32 v22, v22
	v_rndne_f32_e32 v23, v23
	v_fmac_f32_e32 v20, 0x31dc9c88, v16
	v_fmac_f32_e32 v21, 0x31dc9c88, v17
	v_fma_f32 v22, v18, 0.15915494, -v22
	v_fma_f32 v23, v19, 0.15915494, -v23
	v_sin_f32_e32 v16, v20
	v_sin_f32_e32 v17, v21
	v_fmac_f32_e32 v22, 0x31dc9c88, v18
	v_fmac_f32_e32 v23, 0x31dc9c88, v19
	v_cos_f32_e32 v18, v20
	v_cos_f32_e32 v19, v21
	v_pk_mul_f32 v[24:25], v[8:9], v[16:17]
	v_sin_f32_e32 v20, v22
	v_sin_f32_e32 v21, v23
	v_pk_mul_f32 v[8:9], v[8:9], v[18:19]
	v_pk_fma_f32 v[18:19], v[4:5], v[18:19], v[24:25] neg_lo:[0,0,1] neg_hi:[0,0,1]
	v_pk_fma_f32 v[4:5], v[4:5], v[16:17], v[8:9]
	v_pk_mul_f32 v[16:17], v[128:129], v[18:19] op_sel_hi:[0,1]
	v_mul_f32_e32 v18, v129, v28
	v_cos_f32_e32 v22, v22
	v_cos_f32_e32 v23, v23
	v_mul_f32_e32 v19, 0.15915494, v18
	v_rndne_f32_e32 v19, v19
	v_fma_f32 v19, v18, 0.15915494, -v19
	v_pk_mul_f32 v[26:27], v[10:11], v[20:21]
	v_fmac_f32_e32 v19, 0x31dc9c88, v18
	v_pk_fma_f32 v[8:9], v[6:7], v[22:23], v[26:27] neg_lo:[0,0,1] neg_hi:[0,0,1]
	v_pk_mul_f32 v[10:11], v[10:11], v[22:23]
	v_sin_f32_e32 v18, v19
	v_cos_f32_e32 v22, v19
	v_mul_f32_e32 v19, v120, v28
	v_mul_f32_e32 v23, 0.15915494, v19
	v_rndne_f32_e32 v23, v23
	v_fma_f32 v23, v19, 0.15915494, -v23
	v_fmac_f32_e32 v23, 0x31dc9c88, v19
	v_sin_f32_e32 v19, v23
	v_cos_f32_e32 v23, v23
	v_pk_fma_f32 v[6:7], v[6:7], v[20:21], v[10:11]
	v_mul_f32_e32 v20, v112, v28
	v_pk_mul_f32 v[10:11], v[12:13], v[18:19]
	v_pk_mul_f32 v[12:13], v[12:13], v[22:23]
	v_pk_fma_f32 v[10:11], v[0:1], v[22:23], v[10:11] neg_lo:[0,0,1] neg_hi:[0,0,1]
	v_pk_fma_f32 v[0:1], v[0:1], v[18:19], v[12:13]
	v_mul_f32_e32 v21, 0.15915494, v20
	v_pk_mul_f32 v[12:13], v[128:129], v[0:1] op_sel_hi:[0,1]
	v_mul_f32_e32 v1, v113, v28
	v_mul_f32_e32 v19, 0.15915494, v1
	v_rndne_f32_e32 v19, v19
	v_rndne_f32_e32 v21, v21
	v_fma_f32 v19, v1, 0.15915494, -v19
	v_fma_f32 v21, v20, 0.15915494, -v21
	v_fmac_f32_e32 v19, 0x31dc9c88, v1
	v_fmac_f32_e32 v21, 0x31dc9c88, v20
	v_sin_f32_e32 v22, v19
	v_sin_f32_e32 v0, v21
	v_cos_f32_e32 v23, v19
	v_cos_f32_e32 v20, v21
	v_mov_b32_e32 v26, v3
	v_mov_b32_e32 v27, v15
	v_mov_b32_e32 v1, v22
	v_mul_f32_e32 v24, v2, v0
	v_pk_mul_f32 v[26:27], v[26:27], v[22:23]
	v_mov_b32_e32 v21, v23
	v_pk_mul_f32 v[0:1], v[14:15], v[0:1]
	v_mul_f32_e32 v18, v14, v20
	v_pk_fma_f32 v[0:1], v[2:3], v[20:21], v[0:1] neg_lo:[0,0,1] neg_hi:[0,0,1]
	v_mov_b32_e32 v25, v26
	v_mov_b32_e32 v19, v27
	v_pk_mul_f32 v[4:5], v[128:129], v[4:5] op_sel_hi:[0,1]
	v_pk_mul_f32 v[8:9], v[128:129], v[8:9] op_sel_hi:[0,1]
	v_pk_mul_f32 v[6:7], v[128:129], v[6:7] op_sel_hi:[0,1]
	v_pk_mul_f32 v[10:11], v[128:129], v[10:11] op_sel_hi:[0,1]
	v_pk_mul_f32 v[14:15], v[128:129], v[0:1] op_sel_hi:[0,1]
	v_pk_add_f32 v[0:1], v[24:25], v[18:19]
	v_cvt_pk_bf16_f32 v2, v10, v11
	v_pk_mul_f32 v[130:131], v[128:129], v[0:1] op_sel_hi:[0,1]
	v_cvt_pk_bf16_f32 v0, v16, v17
	v_cvt_pk_bf16_f32 v1, v8, v9
	v_cvt_pk_bf16_f32 v3, v14, v15
	v_cvt_pk_bf16_f32 v132, v4, v5
	v_cvt_pk_bf16_f32 v133, v6, v7
	v_cvt_pk_bf16_f32 v134, v12, v13
	global_store_dwordx4 v[142:143], v[0:3], off
	s_branch .LBB0_125
